# v76 + in-proj transposed-store epilogue (V^T tiles): 128 two-byte stores per lane -> 32 eight-byte stores via quad transpose (DPP + v_perm)
# speedup vs baseline: 1.0114x; 1.0050x over previous
.LBB0_406:
	v_add_u32_e32 v142, s3, v176
	v_and_b32_e32 v143, 15, v155
	v_and_b32_e32 v144, 3, v143
	v_lshrrev_b32_e32 v145, 2, v143
	v_sub_u32_e32 v142, v142, v143
	v_lshl_add_u32 v142, v144, 4, v142
	v_lshl_add_u32 v142, v145, 2, v142
	v_mad_u32_u24 v142, s2, v167, v142
	v_lshlrev_b32_e32 v151, 1, v142
	v_and_b32_e32 v146, 1, v144
	v_mov_b32_e32 v147, 0x5040100
	v_mov_b32_e32 v148, 0x3020706
	v_cmp_ne_u32_e32 vcc, 0, v146
	v_cndmask_b32_e32 v150, v147, v148, vcc
	v_and_b32_e32 v146, 2, v144
	v_cmp_ne_u32_e32 vcc, 0, v146
	s_lshl_b32 s68, s2, 1
	s_mov_b32 s66, s0
	s_mov_b32 s67, s1
	v_cvt_pk_bf16_f32 v176, v126, v122
	v_cvt_pk_bf16_f32 v177, v118, v114
	v_cvt_pk_bf16_f32 v178, v62, v58
	v_cvt_pk_bf16_f32 v179, v54, v50
	v_cvt_pk_bf16_f32 v180, v127, v123
	v_cvt_pk_bf16_f32 v181, v119, v115
	v_cvt_pk_bf16_f32 v182, v63, v59
	v_cvt_pk_bf16_f32 v183, v55, v51
	v_mov_b32_dpp v184, v176 quad_perm:[1,0,3,2] row_mask:0xf bank_mask:0xf
	v_mov_b32_dpp v185, v177 quad_perm:[1,0,3,2] row_mask:0xf bank_mask:0xf
	v_mov_b32_dpp v186, v178 quad_perm:[1,0,3,2] row_mask:0xf bank_mask:0xf
	v_mov_b32_dpp v187, v179 quad_perm:[1,0,3,2] row_mask:0xf bank_mask:0xf
	v_mov_b32_dpp v188, v180 quad_perm:[1,0,3,2] row_mask:0xf bank_mask:0xf
	v_mov_b32_dpp v189, v181 quad_perm:[1,0,3,2] row_mask:0xf bank_mask:0xf
	v_mov_b32_dpp v190, v182 quad_perm:[1,0,3,2] row_mask:0xf bank_mask:0xf
	v_mov_b32_dpp v191, v183 quad_perm:[1,0,3,2] row_mask:0xf bank_mask:0xf
	v_perm_b32 v176, v184, v176, v150
	v_perm_b32 v177, v185, v177, v150
	v_perm_b32 v178, v186, v178, v150
	v_perm_b32 v179, v187, v179, v150
	v_perm_b32 v180, v188, v180, v150
	v_perm_b32 v181, v189, v181, v150
	v_perm_b32 v182, v190, v182, v150
	v_perm_b32 v183, v191, v183, v150
	v_cndmask_b32_e32 v184, v177, v176, vcc
	v_cndmask_b32_e32 v186, v179, v178, vcc
	v_cndmask_b32_e32 v188, v181, v180, vcc
	v_cndmask_b32_e32 v190, v183, v182, vcc
	v_mov_b32_dpp v185, v184 quad_perm:[2,3,0,1] row_mask:0xf bank_mask:0xf
	v_mov_b32_dpp v187, v186 quad_perm:[2,3,0,1] row_mask:0xf bank_mask:0xf
	v_mov_b32_dpp v189, v188 quad_perm:[2,3,0,1] row_mask:0xf bank_mask:0xf
	v_mov_b32_dpp v191, v190 quad_perm:[2,3,0,1] row_mask:0xf bank_mask:0xf
	v_cndmask_b32_e32 v192, v176, v185, vcc
	v_cndmask_b32_e32 v193, v185, v177, vcc
	v_cndmask_b32_e32 v194, v178, v187, vcc
	v_cndmask_b32_e32 v195, v187, v179, vcc
	v_cndmask_b32_e32 v196, v180, v189, vcc
	v_cndmask_b32_e32 v197, v189, v181, vcc
	v_cndmask_b32_e32 v198, v182, v191, vcc
	v_cndmask_b32_e32 v199, v191, v183, vcc
	global_store_dwordx2 v151, v[192:193], s[66:67]
	global_store_dwordx2 v151, v[194:195], s[66:67] offset:256
	s_add_u32 s66, s66, s68
	s_addc_u32 s67, s67, 0
	global_store_dwordx2 v151, v[196:197], s[66:67]
	global_store_dwordx2 v151, v[198:199], s[66:67] offset:256
	s_add_u32 s66, s66, s68
	s_addc_u32 s67, s67, 0
	v_cvt_pk_bf16_f32 v200, v128, v124
	v_cvt_pk_bf16_f32 v201, v120, v116
	v_cvt_pk_bf16_f32 v202, v64, v60
	v_cvt_pk_bf16_f32 v203, v56, v52
	v_cvt_pk_bf16_f32 v204, v129, v125
	v_cvt_pk_bf16_f32 v205, v121, v117
	v_cvt_pk_bf16_f32 v206, v65, v61
	v_cvt_pk_bf16_f32 v207, v57, v53
	v_mov_b32_dpp v208, v200 quad_perm:[1,0,3,2] row_mask:0xf bank_mask:0xf
	v_mov_b32_dpp v209, v201 quad_perm:[1,0,3,2] row_mask:0xf bank_mask:0xf
	v_mov_b32_dpp v210, v202 quad_perm:[1,0,3,2] row_mask:0xf bank_mask:0xf
	v_mov_b32_dpp v211, v203 quad_perm:[1,0,3,2] row_mask:0xf bank_mask:0xf
	v_mov_b32_dpp v212, v204 quad_perm:[1,0,3,2] row_mask:0xf bank_mask:0xf
	v_mov_b32_dpp v213, v205 quad_perm:[1,0,3,2] row_mask:0xf bank_mask:0xf
	v_mov_b32_dpp v234, v206 quad_perm:[1,0,3,2] row_mask:0xf bank_mask:0xf
	v_mov_b32_dpp v235, v207 quad_perm:[1,0,3,2] row_mask:0xf bank_mask:0xf
	v_perm_b32 v200, v208, v200, v150
	v_perm_b32 v201, v209, v201, v150
	v_perm_b32 v202, v210, v202, v150
	v_perm_b32 v203, v211, v203, v150
	v_perm_b32 v204, v212, v204, v150
	v_perm_b32 v205, v213, v205, v150
	v_perm_b32 v206, v234, v206, v150
	v_perm_b32 v207, v235, v207, v150
	v_cndmask_b32_e32 v208, v201, v200, vcc
	v_cndmask_b32_e32 v210, v203, v202, vcc
	v_cndmask_b32_e32 v212, v205, v204, vcc
	v_cndmask_b32_e32 v234, v207, v206, vcc
	v_mov_b32_dpp v209, v208 quad_perm:[2,3,0,1] row_mask:0xf bank_mask:0xf
	v_mov_b32_dpp v211, v210 quad_perm:[2,3,0,1] row_mask:0xf bank_mask:0xf
	v_mov_b32_dpp v213, v212 quad_perm:[2,3,0,1] row_mask:0xf bank_mask:0xf
	v_mov_b32_dpp v235, v234 quad_perm:[2,3,0,1] row_mask:0xf bank_mask:0xf
	v_cndmask_b32_e32 v236, v200, v209, vcc
	v_cndmask_b32_e32 v237, v209, v201, vcc
	v_cndmask_b32_e32 v238, v202, v211, vcc
	v_cndmask_b32_e32 v239, v211, v203, vcc
	v_cndmask_b32_e32 v240, v204, v213, vcc
	v_cndmask_b32_e32 v241, v213, v205, vcc
	v_cndmask_b32_e32 v242, v206, v235, vcc
	v_cndmask_b32_e32 v243, v235, v207, vcc
	global_store_dwordx2 v151, v[236:237], s[66:67]
	global_store_dwordx2 v151, v[238:239], s[66:67] offset:256
	s_add_u32 s66, s66, s68
	s_addc_u32 s67, s67, 0
	global_store_dwordx2 v151, v[240:241], s[66:67]
	global_store_dwordx2 v151, v[242:243], s[66:67] offset:256
	s_add_u32 s66, s66, s68
	s_addc_u32 s67, s67, 0
	v_cvt_pk_bf16_f32 v176, v110, v106
	v_cvt_pk_bf16_f32 v177, v102, v98
	v_cvt_pk_bf16_f32 v178, v46, v42
	v_cvt_pk_bf16_f32 v179, v38, v34
	v_cvt_pk_bf16_f32 v180, v111, v107
	v_cvt_pk_bf16_f32 v181, v103, v99
	v_cvt_pk_bf16_f32 v182, v47, v43
	v_cvt_pk_bf16_f32 v183, v39, v35
	v_mov_b32_dpp v184, v176 quad_perm:[1,0,3,2] row_mask:0xf bank_mask:0xf
	v_mov_b32_dpp v185, v177 quad_perm:[1,0,3,2] row_mask:0xf bank_mask:0xf
	v_mov_b32_dpp v186, v178 quad_perm:[1,0,3,2] row_mask:0xf bank_mask:0xf
	v_mov_b32_dpp v187, v179 quad_perm:[1,0,3,2] row_mask:0xf bank_mask:0xf
	v_mov_b32_dpp v188, v180 quad_perm:[1,0,3,2] row_mask:0xf bank_mask:0xf
	v_mov_b32_dpp v189, v181 quad_perm:[1,0,3,2] row_mask:0xf bank_mask:0xf
	v_mov_b32_dpp v190, v182 quad_perm:[1,0,3,2] row_mask:0xf bank_mask:0xf
	v_mov_b32_dpp v191, v183 quad_perm:[1,0,3,2] row_mask:0xf bank_mask:0xf
	v_perm_b32 v176, v184, v176, v150
	v_perm_b32 v177, v185, v177, v150
	v_perm_b32 v178, v186, v178, v150
	v_perm_b32 v179, v187, v179, v150
	v_perm_b32 v180, v188, v180, v150
	v_perm_b32 v181, v189, v181, v150
	v_perm_b32 v182, v190, v182, v150
	v_perm_b32 v183, v191, v183, v150
	v_cndmask_b32_e32 v184, v177, v176, vcc
	v_cndmask_b32_e32 v186, v179, v178, vcc
	v_cndmask_b32_e32 v188, v181, v180, vcc
	v_cndmask_b32_e32 v190, v183, v182, vcc
	v_mov_b32_dpp v185, v184 quad_perm:[2,3,0,1] row_mask:0xf bank_mask:0xf
	v_mov_b32_dpp v187, v186 quad_perm:[2,3,0,1] row_mask:0xf bank_mask:0xf
	v_mov_b32_dpp v189, v188 quad_perm:[2,3,0,1] row_mask:0xf bank_mask:0xf
	v_mov_b32_dpp v191, v190 quad_perm:[2,3,0,1] row_mask:0xf bank_mask:0xf
	v_cndmask_b32_e32 v192, v176, v185, vcc
	v_cndmask_b32_e32 v193, v185, v177, vcc
	v_cndmask_b32_e32 v194, v178, v187, vcc
	v_cndmask_b32_e32 v195, v187, v179, vcc
	v_cndmask_b32_e32 v196, v180, v189, vcc
	v_cndmask_b32_e32 v197, v189, v181, vcc
	v_cndmask_b32_e32 v198, v182, v191, vcc
	v_cndmask_b32_e32 v199, v191, v183, vcc
	global_store_dwordx2 v151, v[192:193], s[66:67]
	global_store_dwordx2 v151, v[194:195], s[66:67] offset:256
	s_add_u32 s66, s66, s68
	s_addc_u32 s67, s67, 0
	global_store_dwordx2 v151, v[196:197], s[66:67]
	global_store_dwordx2 v151, v[198:199], s[66:67] offset:256
	s_add_u32 s66, s66, s68
	s_addc_u32 s67, s67, 0
	v_cvt_pk_bf16_f32 v200, v112, v108
	v_cvt_pk_bf16_f32 v201, v104, v100
	v_cvt_pk_bf16_f32 v202, v48, v44
	v_cvt_pk_bf16_f32 v203, v40, v36
	v_cvt_pk_bf16_f32 v204, v113, v109
	v_cvt_pk_bf16_f32 v205, v105, v101
	v_cvt_pk_bf16_f32 v206, v49, v45
	v_cvt_pk_bf16_f32 v207, v41, v37
	v_mov_b32_dpp v208, v200 quad_perm:[1,0,3,2] row_mask:0xf bank_mask:0xf
	v_mov_b32_dpp v209, v201 quad_perm:[1,0,3,2] row_mask:0xf bank_mask:0xf
	v_mov_b32_dpp v210, v202 quad_perm:[1,0,3,2] row_mask:0xf bank_mask:0xf
	v_mov_b32_dpp v211, v203 quad_perm:[1,0,3,2] row_mask:0xf bank_mask:0xf
	v_mov_b32_dpp v212, v204 quad_perm:[1,0,3,2] row_mask:0xf bank_mask:0xf
	v_mov_b32_dpp v213, v205 quad_perm:[1,0,3,2] row_mask:0xf bank_mask:0xf
	v_mov_b32_dpp v234, v206 quad_perm:[1,0,3,2] row_mask:0xf bank_mask:0xf
	v_mov_b32_dpp v235, v207 quad_perm:[1,0,3,2] row_mask:0xf bank_mask:0xf
	v_perm_b32 v200, v208, v200, v150
	v_perm_b32 v201, v209, v201, v150
	v_perm_b32 v202, v210, v202, v150
	v_perm_b32 v203, v211, v203, v150
	v_perm_b32 v204, v212, v204, v150
	v_perm_b32 v205, v213, v205, v150
	v_perm_b32 v206, v234, v206, v150
	v_perm_b32 v207, v235, v207, v150
	v_cndmask_b32_e32 v208, v201, v200, vcc
	v_cndmask_b32_e32 v210, v203, v202, vcc
	v_cndmask_b32_e32 v212, v205, v204, vcc
	v_cndmask_b32_e32 v234, v207, v206, vcc
	v_mov_b32_dpp v209, v208 quad_perm:[2,3,0,1] row_mask:0xf bank_mask:0xf
	v_mov_b32_dpp v211, v210 quad_perm:[2,3,0,1] row_mask:0xf bank_mask:0xf
	v_mov_b32_dpp v213, v212 quad_perm:[2,3,0,1] row_mask:0xf bank_mask:0xf
	v_mov_b32_dpp v235, v234 quad_perm:[2,3,0,1] row_mask:0xf bank_mask:0xf
	v_cndmask_b32_e32 v236, v200, v209, vcc
	v_cndmask_b32_e32 v237, v209, v201, vcc
	v_cndmask_b32_e32 v238, v202, v211, vcc
	v_cndmask_b32_e32 v239, v211, v203, vcc
	v_cndmask_b32_e32 v240, v204, v213, vcc
	v_cndmask_b32_e32 v241, v213, v205, vcc
	v_cndmask_b32_e32 v242, v206, v235, vcc
	v_cndmask_b32_e32 v243, v235, v207, vcc
	global_store_dwordx2 v151, v[236:237], s[66:67]
	global_store_dwordx2 v151, v[238:239], s[66:67] offset:256
	s_add_u32 s66, s66, s68
	s_addc_u32 s67, s67, 0
	global_store_dwordx2 v151, v[240:241], s[66:67]
	global_store_dwordx2 v151, v[242:243], s[66:67] offset:256
	s_mul_i32 s69, s68, 0x79
	s_add_u32 s66, s66, s69
	s_addc_u32 s67, s67, 0
	v_cvt_pk_bf16_f32 v176, v94, v90
	v_cvt_pk_bf16_f32 v177, v86, v82
	v_cvt_pk_bf16_f32 v178, v30, v26
	v_cvt_pk_bf16_f32 v179, v22, v18
	v_cvt_pk_bf16_f32 v180, v95, v91
	v_cvt_pk_bf16_f32 v181, v87, v83
	v_cvt_pk_bf16_f32 v182, v31, v27
	v_cvt_pk_bf16_f32 v183, v23, v19
	v_mov_b32_dpp v184, v176 quad_perm:[1,0,3,2] row_mask:0xf bank_mask:0xf
	v_mov_b32_dpp v185, v177 quad_perm:[1,0,3,2] row_mask:0xf bank_mask:0xf
	v_mov_b32_dpp v186, v178 quad_perm:[1,0,3,2] row_mask:0xf bank_mask:0xf
	v_mov_b32_dpp v187, v179 quad_perm:[1,0,3,2] row_mask:0xf bank_mask:0xf
	v_mov_b32_dpp v188, v180 quad_perm:[1,0,3,2] row_mask:0xf bank_mask:0xf
	v_mov_b32_dpp v189, v181 quad_perm:[1,0,3,2] row_mask:0xf bank_mask:0xf
	v_mov_b32_dpp v190, v182 quad_perm:[1,0,3,2] row_mask:0xf bank_mask:0xf
	v_mov_b32_dpp v191, v183 quad_perm:[1,0,3,2] row_mask:0xf bank_mask:0xf
	v_perm_b32 v176, v184, v176, v150
	v_perm_b32 v177, v185, v177, v150
	v_perm_b32 v178, v186, v178, v150
	v_perm_b32 v179, v187, v179, v150
	v_perm_b32 v180, v188, v180, v150
	v_perm_b32 v181, v189, v181, v150
	v_perm_b32 v182, v190, v182, v150
	v_perm_b32 v183, v191, v183, v150
	v_cndmask_b32_e32 v184, v177, v176, vcc
	v_cndmask_b32_e32 v186, v179, v178, vcc
	v_cndmask_b32_e32 v188, v181, v180, vcc
	v_cndmask_b32_e32 v190, v183, v182, vcc
	v_mov_b32_dpp v185, v184 quad_perm:[2,3,0,1] row_mask:0xf bank_mask:0xf
	v_mov_b32_dpp v187, v186 quad_perm:[2,3,0,1] row_mask:0xf bank_mask:0xf
	v_mov_b32_dpp v189, v188 quad_perm:[2,3,0,1] row_mask:0xf bank_mask:0xf
	v_mov_b32_dpp v191, v190 quad_perm:[2,3,0,1] row_mask:0xf bank_mask:0xf
	v_cndmask_b32_e32 v192, v176, v185, vcc
	v_cndmask_b32_e32 v193, v185, v177, vcc
	v_cndmask_b32_e32 v194, v178, v187, vcc
	v_cndmask_b32_e32 v195, v187, v179, vcc
	v_cndmask_b32_e32 v196, v180, v189, vcc
	v_cndmask_b32_e32 v197, v189, v181, vcc
	v_cndmask_b32_e32 v198, v182, v191, vcc
	v_cndmask_b32_e32 v199, v191, v183, vcc
	global_store_dwordx2 v151, v[192:193], s[66:67]
	global_store_dwordx2 v151, v[194:195], s[66:67] offset:256
	s_add_u32 s66, s66, s68
	s_addc_u32 s67, s67, 0
	global_store_dwordx2 v151, v[196:197], s[66:67]
	global_store_dwordx2 v151, v[198:199], s[66:67] offset:256
	s_add_u32 s66, s66, s68
	s_addc_u32 s67, s67, 0
	v_cvt_pk_bf16_f32 v200, v96, v92
	v_cvt_pk_bf16_f32 v201, v88, v84
	v_cvt_pk_bf16_f32 v202, v32, v28
	v_cvt_pk_bf16_f32 v203, v24, v20
	v_cvt_pk_bf16_f32 v204, v97, v93
	v_cvt_pk_bf16_f32 v205, v89, v85
	v_cvt_pk_bf16_f32 v206, v33, v29
	v_cvt_pk_bf16_f32 v207, v25, v21
	v_mov_b32_dpp v208, v200 quad_perm:[1,0,3,2] row_mask:0xf bank_mask:0xf
	v_mov_b32_dpp v209, v201 quad_perm:[1,0,3,2] row_mask:0xf bank_mask:0xf
	v_mov_b32_dpp v210, v202 quad_perm:[1,0,3,2] row_mask:0xf bank_mask:0xf
	v_mov_b32_dpp v211, v203 quad_perm:[1,0,3,2] row_mask:0xf bank_mask:0xf
	v_mov_b32_dpp v212, v204 quad_perm:[1,0,3,2] row_mask:0xf bank_mask:0xf
	v_mov_b32_dpp v213, v205 quad_perm:[1,0,3,2] row_mask:0xf bank_mask:0xf
	v_mov_b32_dpp v234, v206 quad_perm:[1,0,3,2] row_mask:0xf bank_mask:0xf
	v_mov_b32_dpp v235, v207 quad_perm:[1,0,3,2] row_mask:0xf bank_mask:0xf
	v_perm_b32 v200, v208, v200, v150
	v_perm_b32 v201, v209, v201, v150
	v_perm_b32 v202, v210, v202, v150
	v_perm_b32 v203, v211, v203, v150
	v_perm_b32 v204, v212, v204, v150
	v_perm_b32 v205, v213, v205, v150
	v_perm_b32 v206, v234, v206, v150
	v_perm_b32 v207, v235, v207, v150
	v_cndmask_b32_e32 v208, v201, v200, vcc
	v_cndmask_b32_e32 v210, v203, v202, vcc
	v_cndmask_b32_e32 v212, v205, v204, vcc
	v_cndmask_b32_e32 v234, v207, v206, vcc
	v_mov_b32_dpp v209, v208 quad_perm:[2,3,0,1] row_mask:0xf bank_mask:0xf
	v_mov_b32_dpp v211, v210 quad_perm:[2,3,0,1] row_mask:0xf bank_mask:0xf
	v_mov_b32_dpp v213, v212 quad_perm:[2,3,0,1] row_mask:0xf bank_mask:0xf
	v_mov_b32_dpp v235, v234 quad_perm:[2,3,0,1] row_mask:0xf bank_mask:0xf
	v_cndmask_b32_e32 v236, v200, v209, vcc
	v_cndmask_b32_e32 v237, v209, v201, vcc
	v_cndmask_b32_e32 v238, v202, v211, vcc
	v_cndmask_b32_e32 v239, v211, v203, vcc
	v_cndmask_b32_e32 v240, v204, v213, vcc
	v_cndmask_b32_e32 v241, v213, v205, vcc
	v_cndmask_b32_e32 v242, v206, v235, vcc
	v_cndmask_b32_e32 v243, v235, v207, vcc
	global_store_dwordx2 v151, v[236:237], s[66:67]
	global_store_dwordx2 v151, v[238:239], s[66:67] offset:256
	s_add_u32 s66, s66, s68
	s_addc_u32 s67, s67, 0
	global_store_dwordx2 v151, v[240:241], s[66:67]
	global_store_dwordx2 v151, v[242:243], s[66:67] offset:256
	s_add_u32 s66, s66, s68
	s_addc_u32 s67, s67, 0
	v_cvt_pk_bf16_f32 v176, v78, v74
	v_cvt_pk_bf16_f32 v177, v70, v66
	v_cvt_pk_bf16_f32 v178, v14, v10
	v_cvt_pk_bf16_f32 v179, v6, v2
	v_cvt_pk_bf16_f32 v180, v79, v75
	v_cvt_pk_bf16_f32 v181, v71, v67
	v_cvt_pk_bf16_f32 v182, v15, v11
	v_cvt_pk_bf16_f32 v183, v7, v3
	v_mov_b32_dpp v184, v176 quad_perm:[1,0,3,2] row_mask:0xf bank_mask:0xf
	v_mov_b32_dpp v185, v177 quad_perm:[1,0,3,2] row_mask:0xf bank_mask:0xf
	v_mov_b32_dpp v186, v178 quad_perm:[1,0,3,2] row_mask:0xf bank_mask:0xf
	v_mov_b32_dpp v187, v179 quad_perm:[1,0,3,2] row_mask:0xf bank_mask:0xf
	v_mov_b32_dpp v188, v180 quad_perm:[1,0,3,2] row_mask:0xf bank_mask:0xf
	v_mov_b32_dpp v189, v181 quad_perm:[1,0,3,2] row_mask:0xf bank_mask:0xf
	v_mov_b32_dpp v190, v182 quad_perm:[1,0,3,2] row_mask:0xf bank_mask:0xf
	v_mov_b32_dpp v191, v183 quad_perm:[1,0,3,2] row_mask:0xf bank_mask:0xf
	v_perm_b32 v176, v184, v176, v150
	v_perm_b32 v177, v185, v177, v150
	v_perm_b32 v178, v186, v178, v150
	v_perm_b32 v179, v187, v179, v150
	v_perm_b32 v180, v188, v180, v150
	v_perm_b32 v181, v189, v181, v150
	v_perm_b32 v182, v190, v182, v150
	v_perm_b32 v183, v191, v183, v150
	v_cndmask_b32_e32 v184, v177, v176, vcc
	v_cndmask_b32_e32 v186, v179, v178, vcc
	v_cndmask_b32_e32 v188, v181, v180, vcc
	v_cndmask_b32_e32 v190, v183, v182, vcc
	v_mov_b32_dpp v185, v184 quad_perm:[2,3,0,1] row_mask:0xf bank_mask:0xf
	v_mov_b32_dpp v187, v186 quad_perm:[2,3,0,1] row_mask:0xf bank_mask:0xf
	v_mov_b32_dpp v189, v188 quad_perm:[2,3,0,1] row_mask:0xf bank_mask:0xf
	v_mov_b32_dpp v191, v190 quad_perm:[2,3,0,1] row_mask:0xf bank_mask:0xf
	v_cndmask_b32_e32 v192, v176, v185, vcc
	v_cndmask_b32_e32 v193, v185, v177, vcc
	v_cndmask_b32_e32 v194, v178, v187, vcc
	v_cndmask_b32_e32 v195, v187, v179, vcc
	v_cndmask_b32_e32 v196, v180, v189, vcc
	v_cndmask_b32_e32 v197, v189, v181, vcc
	v_cndmask_b32_e32 v198, v182, v191, vcc
	v_cndmask_b32_e32 v199, v191, v183, vcc
	global_store_dwordx2 v151, v[192:193], s[66:67]
	global_store_dwordx2 v151, v[194:195], s[66:67] offset:256
	s_add_u32 s66, s66, s68
	s_addc_u32 s67, s67, 0
	global_store_dwordx2 v151, v[196:197], s[66:67]
	global_store_dwordx2 v151, v[198:199], s[66:67] offset:256
	s_add_u32 s66, s66, s68
	s_addc_u32 s67, s67, 0
	v_cvt_pk_bf16_f32 v200, v80, v76
	v_cvt_pk_bf16_f32 v201, v72, v68
	v_cvt_pk_bf16_f32 v202, v16, v12
	v_cvt_pk_bf16_f32 v203, v8, v4
	v_cvt_pk_bf16_f32 v204, v81, v77
	v_cvt_pk_bf16_f32 v205, v73, v69
	v_cvt_pk_bf16_f32 v206, v17, v13
	v_cvt_pk_bf16_f32 v207, v9, v5
	v_mov_b32_dpp v208, v200 quad_perm:[1,0,3,2] row_mask:0xf bank_mask:0xf
	v_mov_b32_dpp v209, v201 quad_perm:[1,0,3,2] row_mask:0xf bank_mask:0xf
	v_mov_b32_dpp v210, v202 quad_perm:[1,0,3,2] row_mask:0xf bank_mask:0xf
	v_mov_b32_dpp v211, v203 quad_perm:[1,0,3,2] row_mask:0xf bank_mask:0xf
	v_mov_b32_dpp v212, v204 quad_perm:[1,0,3,2] row_mask:0xf bank_mask:0xf
	v_mov_b32_dpp v213, v205 quad_perm:[1,0,3,2] row_mask:0xf bank_mask:0xf
	v_mov_b32_dpp v234, v206 quad_perm:[1,0,3,2] row_mask:0xf bank_mask:0xf
	v_mov_b32_dpp v235, v207 quad_perm:[1,0,3,2] row_mask:0xf bank_mask:0xf
	v_perm_b32 v200, v208, v200, v150
	v_perm_b32 v201, v209, v201, v150
	v_perm_b32 v202, v210, v202, v150
	v_perm_b32 v203, v211, v203, v150
	v_perm_b32 v204, v212, v204, v150
	v_perm_b32 v205, v213, v205, v150
	v_perm_b32 v206, v234, v206, v150
	v_perm_b32 v207, v235, v207, v150
	v_cndmask_b32_e32 v208, v201, v200, vcc
	v_cndmask_b32_e32 v210, v203, v202, vcc
	v_cndmask_b32_e32 v212, v205, v204, vcc
	v_cndmask_b32_e32 v234, v207, v206, vcc
	v_mov_b32_dpp v209, v208 quad_perm:[2,3,0,1] row_mask:0xf bank_mask:0xf
	v_mov_b32_dpp v211, v210 quad_perm:[2,3,0,1] row_mask:0xf bank_mask:0xf
	v_mov_b32_dpp v213, v212 quad_perm:[2,3,0,1] row_mask:0xf bank_mask:0xf
	v_mov_b32_dpp v235, v234 quad_perm:[2,3,0,1] row_mask:0xf bank_mask:0xf
	v_cndmask_b32_e32 v236, v200, v209, vcc
	v_cndmask_b32_e32 v237, v209, v201, vcc
	v_cndmask_b32_e32 v238, v202, v211, vcc
	v_cndmask_b32_e32 v239, v211, v203, vcc
	v_cndmask_b32_e32 v240, v204, v213, vcc
	v_cndmask_b32_e32 v241, v213, v205, vcc
	v_cndmask_b32_e32 v242, v206, v235, vcc
	v_cndmask_b32_e32 v243, v235, v207, vcc
	global_store_dwordx2 v151, v[236:237], s[66:67]
	global_store_dwordx2 v151, v[238:239], s[66:67] offset:256
	s_add_u32 s66, s66, s68
	s_addc_u32 s67, s67, 0
	global_store_dwordx2 v151, v[240:241], s[66:67]
	global_store_dwordx2 v151, v[242:243], s[66:67] offset:256
	s_mov_b64 s[0:1], 0

.LBB0_480:
	v_mul_f32_e32 v0, v23, v23
	v_mul_f32_e32 v14, v11, v11
	v_fmac_f32_e32 v0, v22, v22
	v_fmac_f32_e32 v14, v10, v10
	v_fmac_f32_e32 v0, v24, v24
	v_fmac_f32_e32 v14, v12, v12
	v_fmac_f32_e32 v0, v25, v25
	v_fmac_f32_e32 v14, v13, v13
	v_add_f32_e32 v0, v14, v0
	v_mul_f32_e32 v14, v7, v7
	v_fmac_f32_e32 v14, v6, v6
	v_fmac_f32_e32 v14, v8, v8
	v_fmac_f32_e32 v14, v9, v9
	v_add_f32_e32 v0, v14, v0
	v_mul_f32_e32 v14, v3, v3
	v_fmac_f32_e32 v14, v2, v2
	v_fmac_f32_e32 v14, v4, v4
	v_fmac_f32_e32 v14, v5, v5
	v_add_f32_e32 v0, v14, v0
	v_min_i32_e32 v14, 0x8000, v92
	v_ashrrev_i32_e32 v14, 12, v14
	v_mul_i32_i24_e32 v14, 0x1800, v14
	v_ashrrev_i32_e32 v15, 31, v14
	v_lshl_add_u64 v[20:21], v[14:15], 2, s[22:23]
	ds_bpermute_b32 v14, v108, v0
	v_lshl_add_u64 v[18:19], v[20:21], 0, s[10:11]
	v_mov_b32_e32 v85, v1
	v_lshl_add_u64 v[26:27], v[18:19], 0, v[84:85]
	global_load_dwordx4 v[28:31], v[26:27], off
	s_waitcnt lgkmcnt(0)
	v_add_f32_e32 v0, v0, v14
	ds_bpermute_b32 v14, v109, v0
	v_lshl_add_u64 v[26:27], v[20:21], 0, v[84:85]
	global_load_dwordx4 v[32:35], v[26:27], off
	v_ashrrev_i32_e32 v93, 31, v92
	v_lshlrev_b64 v[36:37], 11, v[92:93]
	s_waitcnt lgkmcnt(0)
	v_add_f32_e32 v0, v0, v14
	ds_bpermute_b32 v14, v110, v0
	v_mov_b32_e32 v87, v1
	v_mov_b32_e32 v89, v1
	v_mov_b32_e32 v91, v1
	s_waitcnt lgkmcnt(0)
	v_add_f32_e32 v0, v0, v14
	ds_bpermute_b32 v14, v111, v0
	s_waitcnt lgkmcnt(0)
	v_add_f32_e32 v0, v0, v14
	ds_bpermute_b32 v14, v112, v0
	s_waitcnt lgkmcnt(0)
	v_add_f32_e32 v0, v0, v14
	ds_bpermute_b32 v14, v113, v0
	s_waitcnt lgkmcnt(0)
	v_add_f32_e32 v0, v0, v14
	v_fmamk_f32 v0, v0, 0x3a800000, v218
	v_cmp_gt_f32_e32 vcc, s13, v0
	v_mul_f32_e32 v14, 0x4b800000, v0
	s_nop 0
	v_cndmask_b32_e32 v0, v0, v14, vcc
	v_rsq_f32_e32 v0, v0
	s_nop 0
	v_mul_f32_e32 v14, 0x45800000, v0
	v_cndmask_b32_e32 v0, v0, v14, vcc
	global_load_dwordx4 v[14:17], v[76:77], off
	v_mov_b32_e32 v87, v1
	v_mov_b32_e32 v89, v1
	v_mov_b32_e32 v91, v1
	global_load_dwordx4 v[168:171], v[76:77], off offset:1024
	v_lshl_add_u64 v[172:173], v[18:19], 0, v[86:87]
	global_load_dwordx4 v[172:175], v[172:173], off
	global_load_dwordx4 v[176:179], v[26:27], off offset:1024
	global_load_dwordx4 v[180:183], v[76:77], off offset:2048
	v_lshl_add_u64 v[184:185], v[18:19], 0, v[88:89]
	global_load_dwordx4 v[184:187], v[184:185], off
	global_load_dwordx4 v[188:191], v[26:27], off offset:2048
	global_load_dwordx4 v[192:195], v[76:77], off offset:3072
	v_lshl_add_u64 v[196:197], v[18:19], 0, v[90:91]
	global_load_dwordx4 v[196:199], v[196:197], off
	global_load_dwordx4 v[200:203], v[26:27], off offset:3072
	v_pk_mul_f32 v[20:21], v[24:25], v[0:1] op_sel_hi:[1,0]
	v_pk_mul_f32 v[22:23], v[22:23], v[0:1] op_sel_hi:[1,0]
	v_pk_mul_f32 v[12:13], v[12:13], v[0:1] op_sel_hi:[1,0]
	v_pk_mul_f32 v[10:11], v[10:11], v[0:1] op_sel_hi:[1,0]
	v_pk_mul_f32 v[8:9], v[8:9], v[0:1] op_sel_hi:[1,0]
	v_pk_mul_f32 v[6:7], v[6:7], v[0:1] op_sel_hi:[1,0]
	v_pk_mul_f32 v[4:5], v[4:5], v[0:1] op_sel_hi:[1,0]
	v_pk_mul_f32 v[2:3], v[2:3], v[0:1] op_sel_hi:[1,0]
	s_waitcnt vmcnt(9)
	v_pk_mul_f32 v[14:15], v[14:15], v[22:23]
	v_pk_mul_f32 v[16:17], v[16:17], v[20:21]
	v_pk_add_f32 v[20:21], v[30:31], 1.0 op_sel_hi:[1,0]
	v_pk_add_f32 v[22:23], v[28:29], 1.0 op_sel_hi:[1,0]
	v_pk_fma_f32 v[16:17], v[20:21], v[16:17], v[34:35]
	v_pk_fma_f32 v[14:15], v[22:23], v[14:15], v[32:33]
	v_lshl_add_u64 v[20:21], v[80:81], 0, v[36:37]
	v_cvt_pk_bf16_f32 v14, v14, v15
	v_cvt_pk_bf16_f32 v15, v16, v17
	global_store_dwordx2 v[20:21], v[14:15], off
	v_lshl_add_u64 v[22:23], v[18:19], 0, v[86:87]
	s_waitcnt vmcnt(7)
	v_pk_mul_f32 v[10:11], v[168:169], v[10:11]
	v_pk_mul_f32 v[12:13], v[170:171], v[12:13]
	v_pk_add_f32 v[14:15], v[174:175], 1.0 op_sel_hi:[1, 0]
	v_pk_add_f32 v[16:17], v[172:173], 1.0 op_sel_hi:[1, 0]
	v_pk_fma_f32 v[12:13], v[14:15], v[12:13], v[178:179]
	v_pk_fma_f32 v[10:11], v[16:17], v[10:11], v[176:177]
	v_lshl_add_u64 v[14:15], v[18:19], 0, v[88:89]
	v_cvt_pk_bf16_f32 v10, v10, v11
	v_cvt_pk_bf16_f32 v11, v12, v13
	global_store_dwordx2 v[20:21], v[10:11], off offset:512
	s_waitcnt vmcnt(5)
	v_pk_mul_f32 v[6:7], v[180:181], v[6:7]
	v_pk_mul_f32 v[8:9], v[182:183], v[8:9]
	v_pk_add_f32 v[10:11], v[186:187], 1.0 op_sel_hi:[1, 0]
	v_pk_add_f32 v[12:13], v[184:185], 1.0 op_sel_hi:[1, 0]
	v_pk_fma_f32 v[8:9], v[10:11], v[8:9], v[190:191]
	v_pk_fma_f32 v[6:7], v[12:13], v[6:7], v[188:189]
	v_lshl_add_u64 v[10:11], v[18:19], 0, v[90:91]
	v_cvt_pk_bf16_f32 v6, v6, v7
	v_cvt_pk_bf16_f32 v7, v8, v9
	global_store_dwordx2 v[20:21], v[6:7], off offset:1024
	s_waitcnt vmcnt(3)
	v_pk_mul_f32 v[2:3], v[2:3], v[192:193]
	v_pk_mul_f32 v[4:5], v[4:5], v[194:195]
	v_pk_add_f32 v[6:7], v[198:199], 1.0 op_sel_hi:[1, 0]
	v_pk_add_f32 v[8:9], v[196:197], 1.0 op_sel_hi:[1, 0]
	v_pk_fma_f32 v[4:5], v[4:5], v[6:7], v[202:203]
	v_pk_fma_f32 v[2:3], v[2:3], v[8:9], v[200:201]
	s_nop 0
	v_cvt_pk_bf16_f32 v2, v2, v3
	v_cvt_pk_bf16_f32 v3, v4, v5
	global_store_dwordx2 v[20:21], v[2:3], off offset:1536
	s_branch .LBB0_442
	s_nop 0
	s_nop 0
	s_nop 0
	s_nop 0
	s_nop 0
	s_nop 0
	s_nop 0
	s_nop 0
	s_nop 0
	s_nop 0
	s_nop 0
	s_nop 0
	s_nop 0
	s_nop 0
	s_nop 0
	s_nop 0
	s_nop 0
	s_nop 0
	s_nop 0
	s_nop 0
	s_nop 0
	s_nop 0
	s_nop 0
	s_nop 0
	s_nop 0
	s_nop 0
	s_nop 0
	s_nop 0
	s_nop 0
	s_nop 0
	s_nop 0
	s_nop 0
	s_nop 0
	s_nop 0
	s_nop 0
	s_nop 0
	s_nop 0
	s_nop 0
	s_nop 0
	s_nop 0
	s_nop 0
	s_nop 0
	s_nop 0
	s_nop 0
	s_nop 0
	s_nop 0
	s_nop 0
	s_nop 0
	s_nop 0
	s_nop 0
	s_nop 0
	s_nop 0
	s_nop 0
	s_nop 0
	s_nop 0
	s_nop 0
	s_nop 0
	s_nop 0
	s_nop 0
	s_nop 0
	s_nop 0
	s_nop 0
	s_nop 0
	s_nop 0
	s_nop 0
	s_nop 0
	s_nop 0
	s_nop 0
	s_nop 0
	s_nop 0
	s_nop 0
	s_nop 0
	s_nop 0
	s_nop 0
	s_nop 0
	s_nop 0
	s_nop 0
	s_nop 0
	s_nop 0
	s_nop 0
	s_nop 0
	s_nop 0
	s_nop 0
	s_nop 0
	s_nop 0
	s_nop 0
	s_nop 0
	s_nop 0
	s_nop 0
	s_nop 0
	s_nop 0
	s_nop 0
	s_nop 0
	s_nop 0
	s_nop 0
	s_nop 0
	s_nop 0
	s_nop 0
	s_nop 0
	s_nop 0
	s_nop 0
	s_nop 0
	s_nop 0
	s_nop 0
	s_nop 0
	s_nop 0
	s_nop 0
	s_nop 0
	s_nop 0
	s_nop 0
	s_nop 0
	s_nop 0
	s_nop 0
	s_nop 0
	s_nop 0
	s_nop 0
	s_nop 0
	s_nop 0
	s_nop 0
	s_nop 0
	s_nop 0
	s_nop 0
	s_nop 0
